# v17 plus equal wave priority in the RG-LRU phase (static prio raise for waves 4-7 removed)
# baseline (speedup 1.0000x reference)
; __global__ void __launch_bounds__(512, 2) mega_fwd(Params p) {
;     ...
;     if (__builtin_amdgcn_readfirstlane(threadIdx.x) >= 256) __builtin_amdgcn_s_setprio(1);
;     phase_lru(p, lds);
;     __builtin_amdgcn_s_setprio(0);
.LBB0_621:
	s_or_b64 exec, exec, s[0:1]
	v_readfirstlane_b32 s0, v180
	s_cmpk_lt_i32 s0, 0x100
	s_waitcnt lgkmcnt(0)
	s_barrier
	s_cbranch_scc1 .LBB0_623
	s_nop 0
